# grid barrier: first workgroup of each XCD to arrive starts one early L2 writeback (buffer_wbl2) so the leader's release writeback finds less dirty data; on top of arrival-time invalidate
# speedup vs baseline: 1.0138x; 1.0138x over previous
.Lgs0_b173:
	s_or_b64 exec, exec, s[18:19]
	v_cvt_f32_u32_e32 v4, v2
	s_waitcnt vmcnt(0)
	v_readfirstlane_b32 s18, v3
	v_sub_u32_e32 v3, 0, v2
	v_rcp_iflag_f32_e32 v4, v4
	v_add_u32_e32 v5, s18, v1
	v_mul_f32_e32 v4, 0x4f7ffffe, v4
	v_cvt_u32_f32_e32 v4, v4
	v_mul_lo_u32 v1, v3, v4
	v_mul_hi_u32 v1, v4, v1
	v_add_u32_e32 v1, v4, v1
	v_mul_hi_u32 v1, v5, v1
	v_mul_lo_u32 v3, v1, v2
	v_sub_u32_e32 v3, v5, v3
	v_add_u32_e32 v4, 1, v1
	v_cmp_ge_u32_e32 vcc, v3, v2
	s_nop 1
	v_cndmask_b32_e32 v1, v1, v4, vcc
	v_sub_u32_e32 v4, v3, v2
	v_cndmask_b32_e32 v3, v3, v4, vcc
	v_add_u32_e32 v4, 1, v1
	v_cmp_ge_u32_e32 vcc, v3, v2
	v_add_u32_e32 v3, 1, v5
	s_nop 0
	v_cndmask_b32_e32 v1, v1, v4, vcc
	v_mul_lo_u32 v4, v2, v1
	v_add_u32_e32 v2, v4, v2
	v_cmp_ne_u32_e32 vcc, v3, v2
	s_and_saveexec_b64 s[18:19], vcc
	s_xor_b64 s[18:19], exec, s[18:19]
	s_cbranch_execz .Lgs0_b187
	v_cmp_eq_u32_e32 vcc, v5, v4
	s_cbranch_vccz .Lfw_0
	buffer_wbl2 sc1
.Lfw_0:
	v_readlane_b32 s22, v255, 0
	v_readlane_b32 s23, v255, 1
	s_waitcnt lgkmcnt(0)
	s_nop 3
	global_load_dword v0, v17, s[22:23] sc1
	s_waitcnt vmcnt(0)
	v_cmp_eq_u32_e32 vcc, v0, v1
	s_and_saveexec_b64 s[22:23], vcc
	s_cbranch_execz .Lgs0_b186
	s_mov_b32 s24, 1
	s_mov_b64 s[28:29], 0
	s_branch .Lgs0_b177

.Lfw_4:
	v_readlane_b32 s22, v255, 0
	v_readlane_b32 s23, v255, 1
	s_waitcnt lgkmcnt(0)
	s_nop 3
	global_load_dword v0, v17, s[22:23] sc1
	s_waitcnt vmcnt(0)
	v_cmp_eq_u32_e32 vcc, v0, v1
	s_and_saveexec_b64 s[22:23], vcc
	s_cbranch_execz .LBB0_617
	s_mov_b32 s24, 1
	s_mov_b64 s[26:27], 0
	s_branch .LBB0_608

.LBB0_674:
	s_or_b64 exec, exec, s[14:15]
	v_cvt_f32_u32_e32 v4, v2
	s_waitcnt vmcnt(0)
	v_readfirstlane_b32 s14, v3
	v_sub_u32_e32 v3, 0, v2
	v_rcp_iflag_f32_e32 v4, v4
	v_add_u32_e32 v5, s14, v1
	v_mul_f32_e32 v4, 0x4f7ffffe, v4
	v_cvt_u32_f32_e32 v4, v4
	v_mul_lo_u32 v1, v3, v4
	v_mul_hi_u32 v1, v4, v1
	v_add_u32_e32 v1, v4, v1
	v_mul_hi_u32 v1, v5, v1
	v_mul_lo_u32 v3, v1, v2
	v_sub_u32_e32 v3, v5, v3
	v_add_u32_e32 v4, 1, v1
	v_cmp_ge_u32_e32 vcc, v3, v2
	s_nop 1
	v_cndmask_b32_e32 v1, v1, v4, vcc
	v_sub_u32_e32 v4, v3, v2
	v_cndmask_b32_e32 v3, v3, v4, vcc
	v_add_u32_e32 v4, 1, v1
	v_cmp_ge_u32_e32 vcc, v3, v2
	v_add_u32_e32 v3, 1, v5
	s_nop 0
	v_cndmask_b32_e32 v1, v1, v4, vcc
	v_mul_lo_u32 v4, v2, v1
	v_add_u32_e32 v2, v4, v2
	v_cmp_ne_u32_e32 vcc, v3, v2
	s_and_saveexec_b64 s[14:15], vcc
	s_xor_b64 s[14:15], exec, s[14:15]
	s_cbranch_execz .LBB0_688
	v_cmp_eq_u32_e32 vcc, v5, v4
	s_cbranch_vccz .Lfw_5
	buffer_wbl2 sc1
.Lfw_5:
	v_readlane_b32 s18, v255, 0
	v_readlane_b32 s19, v255, 1
	s_waitcnt lgkmcnt(0)
	s_nop 3
	global_load_dword v0, v17, s[18:19] sc1
	s_waitcnt vmcnt(0)
	v_cmp_eq_u32_e32 vcc, v0, v1
	s_and_saveexec_b64 s[18:19], vcc
	s_cbranch_execz .LBB0_687
	s_mov_b32 s36, 1
	s_mov_b64 s[22:23], 0
	s_branch .LBB0_678

.Lfw_6:
	v_readlane_b32 s18, v255, 0
	v_readlane_b32 s19, v255, 1
	s_waitcnt lgkmcnt(0)
	s_nop 3
	global_load_dword v0, v17, s[18:19] sc1
	s_waitcnt vmcnt(0)
	v_cmp_eq_u32_e32 vcc, v0, v1
	s_and_saveexec_b64 s[18:19], vcc
	s_cbranch_execz .LBB0_755
	s_mov_b32 s24, 1
	s_mov_b64 s[22:23], 0
	s_branch .LBB0_746
